# LDS chunk-parity swizzle also on attention K tile and gemm_stream qkv/pool tiles, on top of gemm8 swizzle
# speedup vs baseline: 1.0492x; 1.0011x over previous
.LBB0_621:
	s_or_b64 exec, exec, s[6:7]
	v_lshlrev_b32_e32 v5, 3, v37
	v_lshlrev_b32_e32 v112, 7, v4
	v_ashrrev_i32_e32 v70, 3, v37
	v_and_b32_e32 v72, 56, v5
	v_lshl_add_u64 v[2:3], s[34:35], 0, v[2:3]
	v_lshlrev_b64 v[4:5], 9, v[110:111]
	v_ashrrev_i32_e32 v113, 31, v112
	v_lshl_add_u64 v[0:1], s[34:35], 0, v[0:1]
	v_lshl_add_u64 v[2:3], v[2:3], 0, v[4:5]
	v_lshlrev_b64 v[4:5], 9, v[112:113]
	v_ashrrev_i32_e32 v71, 31, v70
	v_lshl_add_u64 v[0:1], v[0:1], 0, v[4:5]
	v_lshlrev_b64 v[4:5], 9, v[70:71]
	v_lshl_add_u64 v[2:3], v[2:3], 0, v[4:5]
	v_mov_b32_e32 v99, 0
	v_lshlrev_b32_e32 v98, 1, v72
	v_lshl_add_u64 v[34:35], v[2:3], 0, v[98:99]
	s_movk_i32 s15, 0x4000
	v_add_co_u32_e32 v74, vcc, s15, v34
	s_mov_b32 s29, 0x8000
	s_nop 0
	v_addc_co_u32_e32 v75, vcc, 0, v35, vcc
	v_add_co_u32_e32 v76, vcc, s29, v34
	s_mov_b32 s30, 0xc000
	s_nop 0
	v_addc_co_u32_e32 v77, vcc, 0, v35, vcc
	v_add_co_u32_e32 v78, vcc, s30, v34
	v_lshl_add_u64 v[0:1], v[0:1], 0, v[4:5]
	s_nop 0
	v_addc_co_u32_e32 v79, vcc, 0, v35, vcc
	v_lshl_add_u64 v[32:33], v[0:1], 0, v[98:99]
	global_load_dwordx4 v[38:41], v[34:35], off
	global_load_dwordx4 v[42:45], v[74:75], off
	global_load_dwordx4 v[46:49], v[76:77], off
	global_load_dwordx4 v[50:53], v[78:79], off
	global_load_dwordx4 v[54:57], v[32:33], off
	v_add_co_u32_e32 v80, vcc, s15, v32
	s_add_u32 s16, s34, 0xaa44000
	s_nop 0
	v_addc_co_u32_e32 v81, vcc, 0, v33, vcc
	v_add_co_u32_e32 v82, vcc, s29, v32
	global_load_dwordx4 v[58:61], v[80:81], off
	s_nop 0
	v_addc_co_u32_e32 v83, vcc, 0, v33, vcc
	global_load_dwordx4 v[62:65], v[82:83], off
	v_add_co_u32_e32 v84, vcc, s30, v32
	s_addc_u32 s17, s35, 0
	s_nop 0
	v_addc_co_u32_e32 v85, vcc, 0, v33, vcc
	global_load_dwordx4 v[66:69], v[84:85], off
	global_load_dwordx4 v[0:3], v[34:35], off offset:128
	global_load_dwordx4 v[4:7], v[74:75], off offset:128
	global_load_dwordx4 v[8:11], v[76:77], off offset:128
	global_load_dwordx4 v[12:15], v[78:79], off offset:128
	global_load_dwordx4 v[24:27], v[32:33], off offset:128
	global_load_dwordx4 v[16:19], v[80:81], off offset:128
	global_load_dwordx4 v[20:23], v[82:83], off offset:128
	global_load_dwordx4 v[28:31], v[84:85], off offset:128
	s_movk_i32 s6, 0x90
	v_ashrrev_i32_e32 v74, 1, v37
	s_add_u32 s18, s34, 0xb644000
	v_mul_lo_u32 v75, v70, s6
	v_and_b32_e32 v74, 0xffffffc0, v74
	s_addc_u32 s19, s35, 0
	v_and_b32_e32 v134, 0x4f, v37
	v_bfe_u32 v73, v37, 4, 2
	v_and_or_b32 v76, v37, 15, v74
	v_add3_u32 v132, v96, v75, v98
	v_lshrrev_b32_e32 v251, 3, v37
	v_lshrrev_b32_e32 v250, 1, v251
	v_xor_b32_e32 v250, v251, v250
	v_bfe_u32 v250, v250, 2, 1
	v_bfe_u32 v251, v37, 0, 1
	v_and_b32_e32 v251, v251, v250
	v_lshlrev_b32_e32 v251, 5, v251
	v_lshlrev_b32_e32 v250, 4, v250
	v_sub_u32_e32 v250, v250, v251
	v_add_u32_e32 v132, v132, v250
	s_add_u32 s20, s34, 0xbec4000
	v_mul_u32_u24_e32 v37, 0x48, v134
	v_lshlrev_b64 v[70:71], 8, v[70:71]
	s_addc_u32 s21, s35, 0
	s_lshl_b32 s31, s14, 1
	v_lshlrev_b32_e32 v37, 1, v37
	v_add_u32_e32 v136, 0xd800, v132
	v_lshl_or_b32 v137, v73, 2, v74
	v_add_u32_e32 v138, s31, v36
	s_movk_i32 s33, 0x17f
	s_movk_i32 s42, 0x44
	s_mov_b32 s43, 0x2aaaaaab
	s_movk_i32 s44, 0xffd0
	v_lshlrev_b64 v[100:101], 1, v[70:71]
	v_lshlrev_b32_e32 v98, 1, v72
	s_movk_i32 s45, 0xfff
	s_movk_i32 s48, 0x600
	s_movk_i32 s49, 0x4400
	s_mov_b32 s50, 0xc2fc0000
	v_mov_b32_e32 v139, 0x42800000
	v_not_b32_e32 v140, 63
	v_mov_b64_e32 v[106:107], v[32:33]
	v_mov_b64_e32 v[104:105], v[34:35]
	s_waitcnt vmcnt(15)
	ds_write_b128 v132, v[38:41]
	s_waitcnt vmcnt(14)
	ds_write_b128 v132, v[42:45] offset:4608
	s_waitcnt vmcnt(13)
	ds_write_b128 v132, v[46:49] offset:9216
	s_waitcnt vmcnt(12)
	ds_write_b128 v132, v[50:53] offset:13824
	s_waitcnt vmcnt(11)
	ds_write_b128 v132, v[54:57] offset:36864
	s_waitcnt vmcnt(10)
	ds_write_b128 v132, v[58:61] offset:41472
	s_waitcnt vmcnt(9)
	ds_write_b128 v132, v[62:65] offset:46080
	s_waitcnt vmcnt(8)
	ds_write_b128 v132, v[66:69] offset:50688
	v_mul_lo_u32 v38, v76, s6
	v_lshlrev_b32_e32 v39, 4, v73
	v_lshrrev_b32_e32 v251, 1, v76
	v_xor_b32_e32 v250, v76, v251
	v_bfe_u32 v250, v250, 2, 1
	v_bfe_u32 v251, v73, 0, 1
	v_and_b32_e32 v251, v251, v250
	v_lshlrev_b32_e32 v251, 5, v251
	v_lshlrev_b32_e32 v250, 4, v250
	v_sub_u32_e32 v250, v250, v251
	v_add_u32_e32 v39, v39, v250
	v_add3_u32 v133, v96, v38, v39
	v_add3_u32 v135, v96, v37, v39
	s_mov_b32 s6, s28
	s_waitcnt lgkmcnt(0)
	s_barrier
	s_branch .LBB0_624

.LBB0_916:
	v_ashrrev_i32_e32 v0, 2, v12
	v_bfi_b32 v0, -16, v0, v12
	s_and_b32 s25, s31, 7
	v_add_u32_e32 v90, s6, v0
	v_bfe_u32 v13, v12, 4, 2
	v_mad_i64_i32 v[0:1], s[4:5], v90, s14, v[84:85]
	s_mul_i32 s20, s25, 0xc0
	v_lshl_add_u64 v[0:1], v[0:1], 0, s[20:21]
	v_lshlrev_b32_e32 v86, 4, v13
	v_lshl_add_u64 v[8:9], v[0:1], 0, v[86:87]
	v_lshrrev_b32_e32 v189, 1, v12
	v_xor_b32_e32 v188, v12, v189
	v_bfe_u32 v188, v188, 2, 1
	v_bfe_u32 v189, v12, 4, 1
	v_and_b32_e32 v189, v189, v188
	v_lshlrev_b32_e32 v189, 5, v189
	v_lshlrev_b32_e32 v188, 4, v188
	v_sub_u32_e32 v188, v188, v189
	v_add_u32_e32 v86, v86, v188
	global_load_dwordx4 v[0:3], v[8:9], off
	global_load_dwordx4 v[4:7], v[8:9], off offset:64
	s_nop 0
	global_load_dwordx4 v[8:11], v[8:9], off offset:128
	v_mul_hi_i32 v14, v12, s15
	v_lshrrev_b32_e32 v15, 31, v14
	v_ashrrev_i32_e32 v14, 1, v14
	s_waitcnt vmcnt(3)
	v_add_u32_e32 v28, v14, v15
	v_mad_u64_u32 v[14:15], s[4:5], v28, -12, v[12:13]
	v_add_u32_e32 v18, s24, v28
	v_cmp_gt_i32_e32 vcc, 8, v14
	v_cmp_lt_i32_e64 s[4:5], 7, v14
	v_ashrrev_i32_e32 v19, 31, v18
	s_and_saveexec_b64 s[6:7], s[4:5]
	s_xor_b64 s[4:5], exec, s[6:7]
	v_lshlrev_b64 v[16:17], 6, v[18:19]
	v_lshl_add_u64 v[16:17], s[10:11], 0, v[16:17]
	v_lshl_add_u32 v18, v14, 3, v109
	v_mov_b32_e32 v19, v87
	v_lshl_add_u64 v[92:93], v[18:19], 1, v[16:17]
	s_or_saveexec_b64 s[4:5], s[4:5]
	v_lshlrev_b32_e32 v16, 3, v14
	s_xor_b64 exec, exec, s[4:5]
	v_lshlrev_b64 v[18:19], 10, v[18:19]
	v_lshl_add_u64 v[18:19], s[8:9], 0, v[18:19]
	s_lshl_b32 s20, s25, 7
	v_lshl_add_u64 v[18:19], v[18:19], 0, s[20:21]
	v_ashrrev_i32_e32 v17, 31, v16
	v_lshl_add_u64 v[92:93], v[16:17], 1, v[18:19]
	s_or_b64 exec, exec, s[4:5]
	v_add_u32_e32 v18, 0x200, v12
	v_mul_hi_i32 v15, v18, s15
	v_lshrrev_b32_e32 v17, 31, v15
	v_ashrrev_i32_e32 v15, 1, v15
	v_add_u32_e32 v15, v15, v17
	v_mad_u64_u32 v[18:19], s[4:5], v15, -12, v[18:19]
	v_add_u32_e32 v22, s24, v15
	v_cmp_gt_i32_e64 s[4:5], 8, v18
	v_cmp_lt_i32_e64 s[6:7], 7, v18
	v_ashrrev_i32_e32 v23, 31, v22
	s_and_saveexec_b64 s[36:37], s[6:7]
	s_xor_b64 s[6:7], exec, s[36:37]
	v_lshlrev_b64 v[20:21], 6, v[22:23]
	v_lshl_add_u64 v[20:21], s[10:11], 0, v[20:21]
	v_lshl_add_u32 v22, v18, 3, v109
	v_mov_b32_e32 v23, v87
	v_lshl_add_u64 v[94:95], v[22:23], 1, v[20:21]
	s_or_saveexec_b64 s[6:7], s[6:7]
	v_lshlrev_b32_e32 v20, 3, v18
	s_xor_b64 exec, exec, s[6:7]
	v_lshlrev_b64 v[22:23], 10, v[22:23]
	v_lshl_add_u64 v[22:23], s[8:9], 0, v[22:23]
	s_lshl_b32 s20, s25, 7
	v_lshl_add_u64 v[22:23], v[22:23], 0, s[20:21]
	v_ashrrev_i32_e32 v21, 31, v20
	v_lshl_add_u64 v[94:95], v[20:21], 1, v[22:23]
	s_or_b64 exec, exec, s[6:7]
	v_add_u32_e32 v22, 0x400, v12
	v_mul_hi_i32 v17, v22, s15
	v_lshrrev_b32_e32 v19, 31, v17
	v_ashrrev_i32_e32 v17, 1, v17
	v_add_u32_e32 v17, v17, v19
	v_mad_u64_u32 v[26:27], s[6:7], v17, -12, v[22:23]
	v_add_u32_e32 v24, s24, v17
	v_cmp_lt_i32_e64 s[6:7], 7, v26
	v_ashrrev_i32_e32 v25, 31, v24
	v_lshlrev_b32_e32 v22, 3, v26
	s_and_saveexec_b64 s[36:37], s[6:7]
	s_xor_b64 s[6:7], exec, s[36:37]
	v_lshlrev_b64 v[22:23], 6, v[24:25]
	v_lshl_add_u64 v[24:25], s[10:11], 0, v[22:23]
	v_lshlrev_b32_e32 v22, 3, v26
	v_subrev_u32_e32 v26, 64, v22
	v_mov_b32_e32 v27, v87
	v_lshl_add_u64 v[96:97], v[26:27], 1, v[24:25]
	s_lshl_b32 s20, s25, 6
	s_or_saveexec_b64 s[6:7], s[6:7]
	v_mov_b64_e32 v[100:101], 0x1000
	v_mov_b32_e32 v98, s20
	s_xor_b64 exec, exec, s[6:7]
	v_lshlrev_b64 v[24:25], 10, v[24:25]
	v_lshl_add_u64 v[24:25], s[8:9], 0, v[24:25]
	s_lshl_b32 s20, s25, 7
	s_lshl_b32 s36, s25, 6
	v_lshl_add_u64 v[24:25], v[24:25], 0, s[20:21]
	v_ashrrev_i32_e32 v23, 31, v22
	v_lshl_add_u64 v[96:97], v[22:23], 1, v[24:25]
	v_mov_b64_e32 v[100:101], 0x10000
	v_mov_b32_e32 v98, s36
	s_or_b64 exec, exec, s[6:7]
	v_ashrrev_i32_e32 v19, 4, v12
	v_add_u32_e32 v21, v98, v19
	v_mad_i64_i32 v[24:25], s[6:7], v21, s26, v[88:89]
	v_lshlrev_b32_e32 v21, 3, v12
	s_mov_b32 s25, s21
	v_and_b32_e32 v21, 0x78, v21
	v_lshl_add_u64 v[24:25], s[24:25], 1, v[24:25]
	v_lshlrev_b32_e32 v104, 1, v21
	v_mov_b32_e32 v105, v87
	v_lshl_add_u64 v[106:107], v[24:25], 0, v[104:105]
	v_add_co_u32_e64 v24, s[6:7], s27, v106
	global_load_dwordx4 v[30:33], v[92:93], off
	global_load_dwordx4 v[34:37], v[94:95], off
	global_load_dwordx4 v[38:41], v[96:97], off
	v_addc_co_u32_e64 v25, s[6:7], 0, v107, s[6:7]
	global_load_dwordx4 v[42:45], v[106:107], off
	global_load_dwordx4 v[46:49], v[24:25], off
	v_lshlrev_b32_e32 v102, 3, v13
	v_lshrrev_b32_e32 v189, 1, v28
	v_xor_b32_e32 v188, v28, v189
	v_bfe_u32 v188, v188, 2, 1
	v_bfe_u32 v189, v14, 0, 1
	v_and_b32_e32 v189, v189, v188
	v_lshlrev_b32_e32 v189, 5, v189
	v_lshlrev_b32_e32 v188, 4, v188
	v_sub_u32_e32 v185, v188, v189
	v_lshrrev_b32_e32 v189, 1, v15
	v_xor_b32_e32 v188, v15, v189
	v_bfe_u32 v188, v188, 2, 1
	v_bfe_u32 v189, v18, 0, 1
	v_and_b32_e32 v189, v189, v188
	v_lshlrev_b32_e32 v189, 5, v189
	v_lshlrev_b32_e32 v188, 4, v188
	v_sub_u32_e32 v186, v188, v189
	v_lshrrev_b32_e32 v189, 1, v17
	v_xor_b32_e32 v188, v17, v189
	v_bfe_u32 v188, v188, 2, 1
	v_bfe_u32 v189, v22, 3, 1
	v_and_b32_e32 v189, v189, v188
	v_lshlrev_b32_e32 v189, 5, v189
	v_lshlrev_b32_e32 v188, 4, v188
	v_sub_u32_e32 v187, v188, v189
	v_mul_lo_u32 v13, v28, s28
	v_lshlrev_b32_e32 v14, 4, v14
	v_add_u32_e32 v14, v14, v185
	v_and_b32_e32 v21, 15, v12
	v_mul_lo_u32 v15, v15, s28
	v_lshlrev_b32_e32 v18, 4, v18
	v_add_u32_e32 v18, v18, v186
	v_mul_lo_u32 v17, v17, s28
	v_lshlrev_b32_e32 v99, 1, v22
	v_add_u32_e32 v99, v99, v187
	v_mov_b32_e32 v52, 0
	v_lshl_add_u32 v27, v13, 1, v14
	v_mul_lo_u32 v50, v19, s29
	v_ashrrev_i32_e32 v91, 31, v90
	s_mov_b32 s7, 0
	s_add_i32 s6, s33, -1
	v_cndmask_b32_e64 v108, 12, 16, vcc
	v_cndmask_b32_e64 v110, 12, 16, s[4:5]
	v_mov_b32_e32 v118, 0xf149f2ca
	v_lshlrev_b32_e32 v101, 1, v16
	v_add_u32_e32 v101, v101, v185
	v_lshlrev_b32_e32 v103, 1, v20
	v_add_u32_e32 v103, v103, v186
	v_mov_b32_e32 v12, 0
	v_mov_b32_e32 v16, 0
	v_mov_b32_e32 v20, 0
	v_mov_b32_e32 v24, 0
	v_lshl_add_u32 v28, v15, 1, v18
	v_lshl_add_u32 v29, v17, 1, v99
	v_mul_u32_u24_e32 v105, 0xd0, v21
	v_mul_u32_u24_e32 v111, 0x110, v21
	v_lshlrev_b32_e32 v114, 1, v13
	v_lshlrev_b32_e32 v115, 1, v15
	v_lshlrev_b32_e32 v116, 1, v17
	v_mov_b32_e32 v13, v52
	v_mov_b32_e32 v14, v52
	v_mov_b32_e32 v15, v52
	v_mov_b32_e32 v17, v52
	v_mov_b32_e32 v18, v52
	v_mov_b32_e32 v19, v52
	v_mov_b32_e32 v21, v52
	v_mov_b32_e32 v22, v52
	v_mov_b32_e32 v23, v52
	v_mov_b32_e32 v25, v52
	v_mov_b32_e32 v26, v52
	v_lshlrev_b32_e32 v117, 1, v50
	v_lshl_add_u32 v50, v50, 1, v104
	v_lshl_add_u64 v[112:113], v[106:107], 0, s[22:23]
	s_waitcnt vmcnt(4)
	ds_write_b128 v27, v[30:33]
	s_waitcnt vmcnt(3)
	ds_write_b128 v28, v[34:37]
	s_waitcnt vmcnt(2)
	ds_write_b128 v29, v[38:41]
	s_waitcnt vmcnt(1)
	ds_write_b128 v50, v[42:45] offset:26624
	s_waitcnt vmcnt(0)
	ds_write_b128 v50, v[46:49] offset:35328
	v_mov_b32_e32 v27, v52
	s_waitcnt lgkmcnt(0)
	s_barrier

.LBB0_1324:
	s_cmp_lt_i32 s88, 14
	s_cselect_b64 s[4:5], -1, 0
	s_cmp_gt_i32 s88, 13
	s_cselect_b64 s[6:7], -1, 0
	s_cmp_lt_i32 s89, 14
	s_cselect_b64 s[8:9], -1, 0
	s_or_b64 s[6:7], s[6:7], s[8:9]
	s_and_b64 vcc, exec, s[6:7]
	s_cbranch_vccnz .LBB0_1330
	s_load_dword s12, s[0:1], 0x120
	s_waitcnt lgkmcnt(0)
	s_cmpk_lg_i32 s12, 0x100
	s_cselect_b64 vcc, -1, 0
	s_waitcnt vmcnt(7)
	v_cndmask_b32_e64 v0, 0, 1, vcc
	s_nop 0
	v_readfirstlane_b32 s6, v0
	s_lshl_b32 s60, s2, s6
	s_cmpk_gt_i32 s60, 0x1ff
	s_cbranch_scc1 .LBB0_1330
	v_lshrrev_b32_e32 v79, 8, v204
	v_and_b32_e32 v0, 0x300, v204
	v_cndmask_b32_e32 v90, v0, v79, vcc
	v_add_u32_e32 v0, s60, v90
	v_and_b32_e32 v91, 0xff, v204
	v_min_i32_e32 v0, 0x1ff, v0
	s_add_u32 s6, s34, 0x28c4000
	v_lshlrev_b32_e32 v1, 3, v91
	v_and_b32_e32 v78, 56, v1
	v_lshlrev_b32_e32 v1, 6, v0
	v_and_b32_e32 v1, 0x1c0, v1
	v_ashrrev_i32_e32 v0, 3, v0
	v_add_u32_e32 v1, v1, v0
	s_addc_u32 s7, s35, 0
	v_ashrrev_i32_e32 v70, 7, v1
	v_lshlrev_b32_e32 v1, 6, v1
	s_add_u32 s8, s34, 0x8a44000
	v_and_b32_e32 v80, 0x1f80, v1
	s_addc_u32 s9, s35, 0
	v_lshlrev_b32_e32 v0, 7, v0
	v_lshlrev_b32_e32 v56, 11, v80
	v_mov_b32_e32 v57, 0
	v_lshlrev_b32_e32 v2, 8, v70
	s_add_u32 s10, s34, 0x720000
	v_ashrrev_i32_e32 v76, 3, v91
	v_and_b32_e32 v81, 0x80, v0
	v_lshl_add_u64 v[0:1], s[8:9], 0, v[56:57]
	v_ashrrev_i32_e32 v3, 31, v2
	v_ashrrev_i32_e32 v71, 31, v70
	s_addc_u32 s11, s35, 0
	v_lshl_add_u64 v[0:1], v[2:3], 1, v[0:1]
	v_lshlrev_b64 v[2:3], 17, v[70:71]
	v_ashrrev_i32_e32 v77, 31, v76
	v_lshl_add_u64 v[2:3], s[10:11], 0, v[2:3]
	v_lshlrev_b32_e32 v56, 9, v81
	s_waitcnt vmcnt(6)
	v_lshlrev_b64 v[4:5], 11, v[76:77]
	v_lshl_add_u64 v[2:3], v[2:3], 0, v[56:57]
	v_lshl_add_u64 v[0:1], v[0:1], 0, v[4:5]
	v_lshlrev_b32_e32 v56, 1, v78
	v_lshl_add_u64 v[34:35], v[0:1], 0, v[56:57]
	s_mov_b32 s14, 0x10000
	v_add_co_u32_e32 v58, vcc, s14, v34
	s_mov_b32 s15, 0x20000
	s_nop 0
	v_addc_co_u32_e32 v59, vcc, 0, v35, vcc
	v_add_co_u32_e32 v60, vcc, s15, v34
	s_mov_b32 s33, 0x30000
	s_nop 0
	v_addc_co_u32_e32 v61, vcc, 0, v35, vcc
	v_lshlrev_b64 v[0:1], 9, v[76:77]
	v_add_co_u32_e32 v82, vcc, s33, v34
	v_lshl_add_u64 v[0:1], v[2:3], 0, v[0:1]
	s_nop 0
	v_addc_co_u32_e32 v83, vcc, 0, v35, vcc
	v_lshl_add_u64 v[32:33], v[0:1], 0, v[56:57]
	global_load_dwordx4 v[36:39], v[34:35], off
	global_load_dwordx4 v[40:43], v[58:59], off
	global_load_dwordx4 v[44:47], v[60:61], off
	global_load_dwordx4 v[48:51], v[82:83], off
	global_load_dwordx4 v[52:55], v[32:33], off
	s_movk_i32 s50, 0x4000
	v_add_co_u32_e32 v84, vcc, s50, v32
	s_mov_b32 s51, 0x8000
	s_nop 0
	v_addc_co_u32_e32 v85, vcc, 0, v33, vcc
	v_add_co_u32_e32 v86, vcc, s51, v32
	global_load_dwordx4 v[62:65], v[84:85], off
	s_nop 0
	v_addc_co_u32_e32 v87, vcc, 0, v33, vcc
	s_mov_b32 s52, 0xc000
	global_load_dwordx4 v[66:69], v[86:87], off
	v_add_co_u32_e32 v88, vcc, s52, v32
	s_movk_i32 s13, 0x90
	s_nop 0
	v_addc_co_u32_e32 v89, vcc, 0, v33, vcc
	global_load_dwordx4 v[72:75], v[88:89], off
	global_load_dwordx4 v[0:3], v[34:35], off offset:128
	global_load_dwordx4 v[4:7], v[58:59], off offset:128
	global_load_dwordx4 v[8:11], v[60:61], off offset:128
	global_load_dwordx4 v[12:15], v[82:83], off offset:128
	global_load_dwordx4 v[16:19], v[32:33], off offset:128
	global_load_dwordx4 v[20:23], v[84:85], off offset:128
	global_load_dwordx4 v[24:27], v[86:87], off offset:128
	global_load_dwordx4 v[28:31], v[88:89], off offset:128
	v_mul_u32_u24_e32 v79, 0x12000, v79
	v_mul_lo_u32 v71, v76, s13
	v_add3_u32 v71, v79, v71, v56
	v_lshrrev_b32_e32 v250, 1, v76
	v_xor_b32_e32 v250, v76, v250
	v_bfe_u32 v250, v250, 2, 1
	v_bfe_u32 v251, v91, 0, 1
	v_and_b32_e32 v251, v251, v250
	v_lshlrev_b32_e32 v251, 5, v251
	v_lshlrev_b32_e32 v250, 4, v250
	v_sub_u32_e32 v250, v250, v251
	v_add_u32_e32 v71, v71, v250
	v_bfe_u32 v82, v91, 4, 2
	s_lshl_b32 s53, s12, 1
	v_lshlrev_b64 v[58:59], 10, v[76:77]
	v_lshlrev_b64 v[60:61], 8, v[76:77]
	v_add_u32_e32 v77, s53, v90
	s_movk_i32 s54, 0x1000
	s_mov_b64 s[16:17], 0x1800
	s_mov_b64 s[18:19], 0x8000
	s_mov_b64 s[20:21], 0x8800
	s_mov_b64 s[22:23], 0x9000
	s_mov_b32 s55, 0x9000
	s_mov_b64 s[24:25], 0x9800
	s_mov_b64 s[26:27], 0x10000
	s_mov_b64 s[28:29], 0x10800
	s_mov_b64 s[30:31], 0x11000
	s_mov_b32 s56, 0x11000
	s_waitcnt vmcnt(15)
	ds_write_b128 v71, v[36:39]
	s_waitcnt vmcnt(14)
	ds_write_b128 v71, v[40:43] offset:4608
	s_waitcnt vmcnt(13)
	ds_write_b128 v71, v[44:47] offset:9216
	s_waitcnt vmcnt(12)
	ds_write_b128 v71, v[48:51] offset:13824
	s_waitcnt vmcnt(11)
	ds_write_b128 v71, v[52:55] offset:36864
	s_waitcnt vmcnt(10)
	ds_write_b128 v71, v[62:65] offset:41472
	s_waitcnt vmcnt(9)
	ds_write_b128 v71, v[66:69] offset:46080
	s_waitcnt vmcnt(8)
	ds_write_b128 v71, v[72:75] offset:50688
	v_ashrrev_i32_e32 v36, 1, v91
	v_and_b32_e32 v36, 0xffffffc0, v36
	v_and_or_b32 v37, v91, 15, v36
	v_mul_lo_u32 v37, v37, s13
	v_lshlrev_b32_e32 v38, 4, v82
	v_lshrrev_b32_e32 v251, 1, v91
	v_xor_b32_e32 v250, v91, v251
	v_bfe_u32 v250, v250, 2, 1
	v_bfe_u32 v251, v82, 0, 1
	v_and_b32_e32 v251, v251, v250
	v_lshlrev_b32_e32 v251, 5, v251
	v_lshlrev_b32_e32 v250, 4, v250
	v_sub_u32_e32 v250, v250, v251
	v_add_u32_e32 v38, v38, v250
	v_and_b32_e32 v73, 0x4f, v91
	v_add3_u32 v72, v79, v37, v38
	v_mul_u32_u24_e32 v37, 0x48, v73
	v_lshlrev_b32_e32 v37, 1, v37
	v_add3_u32 v74, v79, v37, v38
	v_add_u32_e32 v75, 0xd800, v71
	v_lshl_or_b32 v76, v82, 2, v36
	v_lshlrev_b32_e32 v62, 1, v78
	s_mov_b64 s[12:13], 0x1000
	s_mov_b64 s[36:37], 0x11800
	s_mov_b64 s[38:39], 0x18000
	s_mov_b32 s57, 0x18000
	s_mov_b64 s[40:41], 0x18800
	s_mov_b64 s[42:43], 0x19000
	s_mov_b32 s58, 0x19000
	s_mov_b64 s[44:45], 0x19800
	v_mov_b64_e32 v[64:65], v[34:35]
	v_mov_b64_e32 v[66:67], v[32:33]
	s_waitcnt lgkmcnt(0)
	s_barrier
	s_branch .LBB0_1328
